# stack22: attention tile loop without per-group s_setprio flips, one static raise for waves 4-7 per unit (on top of stack21)
# speedup vs baseline: 1.0037x; 1.0026x over previous
; #define LDS_WAIT() asm volatile("s_waitcnt lgkmcnt(0)" ::: "memory")
; DI unsigned short f2bf(float f) { return (unsigned short)(pg8::cvt_pk_bf16(f, 0.f) & 0xffffu); }
; DI float half_sum(float x) { const auto rr = __builtin_amdgcn_permlane32_swap(__float_as_uint(x), __float_as_uint(x), false, false); return __uint_as_float(rr[0]) + __uint_as_float(rr[1]); }
; DI int crow(int r, int h) { return (r & 3) + 8 * (r >> 2) + 4 * h; }
; DI void attn_unit(const bf16_t* Qb, const bf16_t* Kb, const bf16_t* Vt, bf16_t* MIX, int b, int h, int qb, char* lds, int tid_in) {
;     ...
;     l_run = half_sum(l_run);
;     if (hh == 0) wsf[r] = 1.f / l_run;
;     LDS_WAIT();
;     bf16_t* op = MIX + (rowbase + q0 + 32 * wave) * DM + h * 64;
;     const int ob = 4 * hh * DM + r;
; #pragma unroll
;     for (int i = 0; i < 16; ++i) { const int q = crow(i, hh); const float f = wsf[q]; const int oi = ob + ((i & 3) + 8 * (i >> 2)) * DM; op[oi] = f2bf(o0[i] * f); op[oi + 32] = f2bf(o1[i] * f); }
;     __syncthreads();
.LBB0_444:
	s_or_b64 exec, exec, s[52:53]
	s_setprio 0
	s_waitcnt lgkmcnt(0)
	ds_read_b128 v[190:193], v149
	ds_read_b128 v[194:197], v149 offset:32
	ds_read_b128 v[198:201], v149 offset:64
	ds_read_b128 v[212:215], v149 offset:96
	s_waitcnt lgkmcnt(0)
	v_lshlrev_b64 v[34:35], 11, v[146:147]
	v_lshl_or_b32 v36, v165, 12, v164
	v_lshl_add_u64 v[34:35], s[46:47], 0, v[34:35]
	v_ashrrev_i32_e32 v37, 31, v36
	v_mul_f32_e32 v18, v18, v190
	v_lshl_add_u64 v[34:35], v[36:37], 1, v[34:35]
	v_mul_f32_e32 v0, v2, v190
	v_cvt_pk_bf16_f32 v18, v18, v1
	global_store_short v[34:35], v18, off
	v_cvt_pk_bf16_f32 v0, v0, v1
	global_store_short v[34:35], v0, off offset:64
	s_movk_i32 s2, 0x1000
	s_add_i32 s37, s37, 1
	s_cmp_eq_u32 s37, 4
	v_mul_f32_e32 v0, v19, v191
	v_cvt_pk_bf16_f32 v0, v0, v1
	global_store_short v[34:35], v0, off offset:2048
	v_mul_f32_e32 v0, v3, v191
	v_cvt_pk_bf16_f32 v0, v0, v1
	global_store_short v[34:35], v0, off offset:2112
	v_add_co_u32_e32 v2, vcc, s2, v34
	s_movk_i32 s2, 0x5000
	v_mul_f32_e32 v0, v20, v192
	v_cvt_pk_bf16_f32 v0, v0, v1
	v_addc_co_u32_e32 v3, vcc, 0, v35, vcc
	global_store_short v[2:3], v0, off
	v_mul_f32_e32 v0, v4, v192
	v_cvt_pk_bf16_f32 v0, v0, v1
	global_store_short v[2:3], v0, off offset:64
	v_mul_f32_e32 v0, v21, v193
	v_cvt_pk_bf16_f32 v0, v0, v1
	global_store_short v[2:3], v0, off offset:2048
	v_mul_f32_e32 v0, v5, v193
	v_cvt_pk_bf16_f32 v0, v0, v1
	global_store_short v[2:3], v0, off offset:2112
	v_add_co_u32_e32 v2, vcc, s2, v34
	s_mov_b32 s2, 0x9000
	v_mul_f32_e32 v0, v22, v194
	v_cvt_pk_bf16_f32 v0, v0, v1
	v_addc_co_u32_e32 v3, vcc, 0, v35, vcc
	global_store_short v[2:3], v0, off offset:-4096
	v_mul_f32_e32 v0, v6, v194
	v_cvt_pk_bf16_f32 v0, v0, v1
	v_add_co_u32_e32 v4, vcc, s25, v34
	s_nop 1
	v_addc_co_u32_e32 v5, vcc, 0, v35, vcc
	global_store_short v[4:5], v0, off offset:64
	v_mul_f32_e32 v0, v23, v195
	v_cvt_pk_bf16_f32 v0, v0, v1
	global_store_short v[4:5], v0, off offset:2048
	v_mul_f32_e32 v0, v7, v195
	v_cvt_pk_bf16_f32 v0, v0, v1
	global_store_short v[4:5], v0, off offset:2112
	v_mul_f32_e32 v0, v24, v196
	v_cvt_pk_bf16_f32 v0, v0, v1
	global_store_short v[2:3], v0, off
	v_mul_f32_e32 v0, v8, v196
	v_cvt_pk_bf16_f32 v0, v0, v1
	global_store_short v[2:3], v0, off offset:64
	v_mul_f32_e32 v0, v25, v197
	v_cvt_pk_bf16_f32 v0, v0, v1
	global_store_short v[2:3], v0, off offset:2048
	v_mul_f32_e32 v0, v9, v197
	v_cvt_pk_bf16_f32 v0, v0, v1
	global_store_short v[2:3], v0, off offset:2112
	v_add_co_u32_e32 v2, vcc, s2, v34
	s_mov_b32 s2, 0x8000
	v_mul_f32_e32 v0, v26, v198
	v_cvt_pk_bf16_f32 v0, v0, v1
	v_addc_co_u32_e32 v3, vcc, 0, v35, vcc
	global_store_short v[2:3], v0, off offset:-4096
	v_mul_f32_e32 v0, v10, v198
	v_cvt_pk_bf16_f32 v0, v0, v1
	v_add_co_u32_e32 v4, vcc, s2, v34
	s_mov_b32 s2, 0xd000
	s_nop 0
	v_addc_co_u32_e32 v5, vcc, 0, v35, vcc
	global_store_short v[4:5], v0, off offset:64
	v_mul_f32_e32 v0, v27, v199
	v_cvt_pk_bf16_f32 v0, v0, v1
	global_store_short v[4:5], v0, off offset:2048
	v_mul_f32_e32 v0, v11, v199
	v_cvt_pk_bf16_f32 v0, v0, v1
	global_store_short v[4:5], v0, off offset:2112
	v_mul_f32_e32 v0, v28, v200
	v_cvt_pk_bf16_f32 v0, v0, v1
	global_store_short v[2:3], v0, off
	v_mul_f32_e32 v0, v12, v200
	v_cvt_pk_bf16_f32 v0, v0, v1
	global_store_short v[2:3], v0, off offset:64
	v_mul_f32_e32 v0, v29, v201
	v_cvt_pk_bf16_f32 v0, v0, v1
	global_store_short v[2:3], v0, off offset:2048
	v_mul_f32_e32 v0, v13, v201
	v_cvt_pk_bf16_f32 v0, v0, v1
	global_store_short v[2:3], v0, off offset:2112
	v_add_co_u32_e32 v2, vcc, s2, v34
	s_mov_b32 s2, 0xc000
	v_mul_f32_e32 v0, v30, v212
	v_cvt_pk_bf16_f32 v0, v0, v1
	v_addc_co_u32_e32 v3, vcc, 0, v35, vcc
	global_store_short v[2:3], v0, off offset:-4096
	v_mul_f32_e32 v0, v14, v212
	v_cvt_pk_bf16_f32 v0, v0, v1
	v_add_co_u32_e32 v4, vcc, s2, v34
	s_nop 1
	v_addc_co_u32_e32 v5, vcc, 0, v35, vcc
	global_store_short v[4:5], v0, off offset:64
	v_mul_f32_e32 v0, v31, v213
	v_cvt_pk_bf16_f32 v0, v0, v1
	global_store_short v[4:5], v0, off offset:2048
	v_mul_f32_e32 v0, v15, v213
	v_cvt_pk_bf16_f32 v0, v0, v1
	global_store_short v[4:5], v0, off offset:2112
	v_mul_f32_e32 v0, v32, v214
	v_cvt_pk_bf16_f32 v0, v0, v1
	global_store_short v[2:3], v0, off
	v_mul_f32_e32 v0, v16, v214
	v_cvt_pk_bf16_f32 v0, v0, v1
	global_store_short v[2:3], v0, off offset:64
	v_mul_f32_e32 v0, v33, v215
	v_cvt_pk_bf16_f32 v0, v0, v1
	global_store_short v[2:3], v0, off offset:2048
	v_mul_f32_e32 v0, v17, v215
	v_cvt_pk_bf16_f32 v0, v0, v1
	global_store_short v[2:3], v0, off offset:2112
	s_barrier
	s_cbranch_scc1 .LBB0_442

; DI int opaque_lane() { int l; asm volatile("v_mbcnt_lo_u32_b32 %0, -1, 0\n\tv_mbcnt_hi_u32_b32 %0, -1, %0" : "=v"(l)); return l; }
; DI void attn_unit(const bf16_t* Qb, const bf16_t* Kb, const bf16_t* Vt, bf16_t* MIX, int b, int h, int qb, char* lds, int tid_in) {
;     const int lane = opaque_lane(), wave = tid_in >> 6, tid = wave * 64 + lane, r = lane & 31, hh = lane >> 5;
;     const size_t rowbase = (size_t)b * SEQ; const int q0 = qb * 256;
.LBB0_450:
	v_readlane_b32 s100, v243, 63
	v_readlane_b32 s101, v242, 0
	s_cmp_lg_u64 s[100:101], 0
	s_cbranch_scc1 .Lattn_prio_done
	s_setprio 1

; DI int crow(int r, int h) { return (r & 3) + 8 * (r >> 2) + 4 * h; }
; #define MFMA32(a, b, c) __builtin_amdgcn_mfma_f32_32x32x16_bf16((a), (b), (c), 0, 0, 0)
; DI void attn_unit(const bf16_t* Qb, const bf16_t* Kb, const bf16_t* Vt, bf16_t* MIX, int b, int h, int qb, char* lds, int tid_in) {
;     ...
;         if (kv0 <= q0 + 32 * wave + 31) {
;             const char* kb_ = lds + buf * ABUF; const char* vb_ = kb_ + AK_BYTES;
;             f32x16 p[4];
;             f32x16 negm;
; #pragma unroll
;             for (int i = 0; i < 16; ++i) negm[i] = -m_run;
; #pragma unroll
;             for (int kb = 0; kb < 4; ++kb) p[kb] = negm;
;             {
;                 bf16x8 kf[2][4];
; #pragma unroll
;                 for (int kb = 0; kb < 4; ++kb) kf[0][kb] = *(const bf16x8*)(kb_ + hh * 2048 + (32 * kb + r) * 16);
; #pragma unroll
;                 for (int ds = 0; ds < 6; ++ds) {
;                     if (ds + 1 < 6) {
; #pragma unroll
;                         for (int kb = 0; kb < 4; ++kb) kf[(ds + 1) & 1][kb] = *(const bf16x8*)(kb_ + (2 * (ds + 1) + hh) * 2048 + (32 * kb + r) * 16); }
;                     __builtin_amdgcn_sched_barrier(0);
;                     __builtin_amdgcn_s_setprio(1);
; #pragma unroll
;                     for (int kb = 0; kb < 4; ++kb) p[kb] = MFMA32(kf[ds & 1][kb], qr[ds], p[kb]);
;                     __builtin_amdgcn_s_setprio(0);
;                     __builtin_amdgcn_sched_barrier(0);
;                 }
;             }
;             if (kv0 + 127 > q0 + 32 * wave) {
; #pragma unroll
;                 for (int kb = 0; kb < 4; ++kb)
; #pragma unroll
;                     for (int i = 0; i < 16; ++i) { const int kv = kv0 + 32 * kb + crow(i, hh); if (kv > qabs) p[kb][i] = -1e30f; }
.LBB0_454:
	s_add_i32 s2, s60, -1
	s_and_b32 s78, s2, 1
	v_cmp_le_i32_e32 vcc, s74, v171
	s_and_saveexec_b64 s[54:55], vcc
	s_cbranch_execz .LBB0_468
	s_mul_i32 s2, s78, 0xa400
	s_add_i32 s16, s2, 0
	v_add3_u32 v211, s16, v172, v173
	v_xor_b32_e32 v250, 32, v211
	v_xor_b32_e32 v251, 64, v211
	v_xor_b32_e32 v252, 0x60, v211
	ds_read_b128 v[50:53], v211
	ds_read_b128 v[54:57], v211 offset:512
	ds_read_b128 v[190:193], v211 offset:1024
	ds_read_b128 v[194:197], v211 offset:1536
	ds_read_b128 v[198:201], v250 offset:4096
	ds_read_b128 v[212:215], v250 offset:4608
	ds_read_b128 v[216:219], v250 offset:5120
	ds_read_b128 v[220:223], v250 offset:5632
	v_xor_b32_e32 v34, 0x80000000, v177
	v_mov_b32_e32 v35, v34
	v_mov_b32_e32 v36, v34
	v_mov_b32_e32 v37, v34
	v_mov_b32_e32 v38, v34
	v_mov_b32_e32 v39, v34
	v_mov_b32_e32 v40, v34
	v_mov_b32_e32 v41, v34
	v_mov_b32_e32 v42, v34
	v_mov_b32_e32 v43, v34
	v_mov_b32_e32 v44, v34
	v_mov_b32_e32 v45, v34
	v_mov_b32_e32 v46, v34
	v_mov_b32_e32 v47, v34
	v_mov_b32_e32 v48, v34
	v_mov_b32_e32 v49, v34
	s_waitcnt lgkmcnt(7)
	v_mfma_f32_32x32x16_bf16 v[82:97], v[50:53], v[118:121], v[34:49]
	s_waitcnt lgkmcnt(6)
	v_mfma_f32_32x32x16_bf16 v[66:81], v[54:57], v[118:121], v[34:49]
	s_waitcnt lgkmcnt(5)
	v_mfma_f32_32x32x16_bf16 v[50:65], v[190:193], v[118:121], v[34:49]
	s_waitcnt lgkmcnt(4)
	v_mfma_f32_32x32x16_bf16 v[34:49], v[194:197], v[118:121], v[34:49]
	ds_read_b128 v[190:193], v251 offset:8192
	ds_read_b128 v[194:197], v251 offset:8704
	ds_read_b128 v[224:227], v251 offset:9216
	ds_read_b128 v[228:231], v251 offset:9728
	s_waitcnt lgkmcnt(7)
	v_mfma_f32_32x32x16_bf16 v[82:97], v[198:201], v[122:125], v[82:97]
	s_waitcnt lgkmcnt(6)
	v_mfma_f32_32x32x16_bf16 v[66:81], v[212:215], v[122:125], v[66:81]
	s_waitcnt lgkmcnt(5)
	v_mfma_f32_32x32x16_bf16 v[50:65], v[216:219], v[122:125], v[50:65]
	s_waitcnt lgkmcnt(4)
	v_mfma_f32_32x32x16_bf16 v[34:49], v[220:223], v[122:125], v[34:49]
	ds_read_b128 v[198:201], v252 offset:12288
	ds_read_b128 v[212:215], v252 offset:12800
	ds_read_b128 v[216:219], v252 offset:13312
	ds_read_b128 v[220:223], v252 offset:13824
	s_waitcnt lgkmcnt(7)
	v_mfma_f32_32x32x16_bf16 v[82:97], v[190:193], v[126:129], v[82:97]
	s_waitcnt lgkmcnt(6)
	v_mfma_f32_32x32x16_bf16 v[66:81], v[194:197], v[126:129], v[66:81]
	s_waitcnt lgkmcnt(5)
	v_mfma_f32_32x32x16_bf16 v[50:65], v[224:227], v[126:129], v[50:65]
	s_waitcnt lgkmcnt(4)
	v_mfma_f32_32x32x16_bf16 v[34:49], v[228:231], v[126:129], v[34:49]
	ds_read_b128 v[190:193], v211 offset:16384
	ds_read_b128 v[194:197], v211 offset:16896
	ds_read_b128 v[224:227], v211 offset:17408
	ds_read_b128 v[228:231], v211 offset:17920
	s_waitcnt lgkmcnt(7)
	v_mfma_f32_32x32x16_bf16 v[82:97], v[198:201], v[130:133], v[82:97]
	s_waitcnt lgkmcnt(6)
	v_mfma_f32_32x32x16_bf16 v[66:81], v[212:215], v[130:133], v[66:81]
	s_waitcnt lgkmcnt(5)
	v_mfma_f32_32x32x16_bf16 v[50:65], v[216:219], v[130:133], v[50:65]
	s_waitcnt lgkmcnt(4)
	v_mfma_f32_32x32x16_bf16 v[34:49], v[220:223], v[130:133], v[34:49]
	ds_read_b128 v[198:201], v250 offset:20480
	ds_read_b128 v[212:215], v250 offset:20992
	ds_read_b128 v[216:219], v250 offset:21504
	ds_read_b128 v[220:223], v250 offset:22016
	s_waitcnt lgkmcnt(7)
	v_mfma_f32_32x32x16_bf16 v[82:97], v[190:193], v[134:137], v[82:97]
	s_waitcnt lgkmcnt(6)
	v_mfma_f32_32x32x16_bf16 v[66:81], v[194:197], v[134:137], v[66:81]
	s_waitcnt lgkmcnt(5)
	v_mfma_f32_32x32x16_bf16 v[50:65], v[224:227], v[134:137], v[50:65]
	s_waitcnt lgkmcnt(4)
	v_mfma_f32_32x32x16_bf16 v[34:49], v[228:231], v[134:137], v[34:49]
	s_waitcnt lgkmcnt(3)
	v_mfma_f32_32x32x16_bf16 v[82:97], v[198:201], v[138:141], v[82:97]
	s_waitcnt lgkmcnt(2)
	v_mfma_f32_32x32x16_bf16 v[66:81], v[212:215], v[138:141], v[66:81]
	s_waitcnt lgkmcnt(1)
	v_mfma_f32_32x32x16_bf16 v[50:65], v[216:219], v[138:141], v[50:65]
	s_waitcnt lgkmcnt(0)
	v_mfma_f32_32x32x16_bf16 v[34:49], v[220:223], v[138:141], v[34:49]
	s_add_i32 s2, s74, 0x7f
	v_cmp_gt_i32_e32 vcc, s2, v166
	s_and_saveexec_b64 s[56:57], vcc
	s_cbranch_execz .LBB0_457
	v_add_u32_e32 v190, s74, v174
	v_cmp_lt_i32_e32 vcc, v190, v170
	v_add_u32_e32 v191, 2, v190
	s_nop 0
	v_cndmask_b32_e32 v83, v208, v83, vcc
	v_cmp_le_i32_e32 vcc, v190, v170
	s_nop 1
	v_cndmask_b32_e32 v82, v208, v82, vcc
	v_cmp_le_i32_e32 vcc, v191, v170
	v_add_u32_e32 v191, 3, v190
	s_nop 0
	v_cndmask_b32_e32 v84, v208, v84, vcc
	v_cmp_le_i32_e32 vcc, v191, v170
	v_add_u32_e32 v191, 8, v190
	s_nop 0
	v_cndmask_b32_e32 v85, v208, v85, vcc
	v_cmp_le_i32_e32 vcc, v191, v170
	v_add_u32_e32 v191, 9, v190
	s_nop 0
	v_cndmask_b32_e32 v86, v208, v86, vcc
	v_cmp_le_i32_e32 vcc, v191, v170
	v_add_u32_e32 v191, 10, v190
	s_nop 0
	v_cndmask_b32_e32 v87, v208, v87, vcc
	v_cmp_le_i32_e32 vcc, v191, v170
	v_add_u32_e32 v191, 11, v190
	s_nop 0
	v_cndmask_b32_e32 v88, v208, v88, vcc
	v_cmp_le_i32_e32 vcc, v191, v170
	v_add_u32_e32 v191, 16, v190
	s_nop 0
	v_cndmask_b32_e32 v89, v208, v89, vcc
	v_cmp_le_i32_e32 vcc, v191, v170
	v_add_u32_e32 v191, 17, v190
	s_nop 0
	v_cndmask_b32_e32 v90, v208, v90, vcc
	v_cmp_le_i32_e32 vcc, v191, v170
	v_add_u32_e32 v191, 18, v190
	s_nop 0
	v_cndmask_b32_e32 v91, v208, v91, vcc
	v_cmp_le_i32_e32 vcc, v191, v170
	v_add_u32_e32 v191, 19, v190
	s_nop 0
	v_cndmask_b32_e32 v92, v208, v92, vcc
	v_cmp_le_i32_e32 vcc, v191, v170
	v_add_u32_e32 v191, 24, v190
	s_nop 0
	v_cndmask_b32_e32 v93, v208, v93, vcc
	v_cmp_le_i32_e32 vcc, v191, v170
	v_add_u32_e32 v191, 25, v190
	s_nop 0
	v_cndmask_b32_e32 v94, v208, v94, vcc
	v_cmp_le_i32_e32 vcc, v191, v170
	v_add_u32_e32 v191, 26, v190
	s_nop 0
; DI int crow(int r, int h) { return (r & 3) + 8 * (r >> 2) + 4 * h; }
; DI void attn_unit(const bf16_t* Qb, const bf16_t* Kb, const bf16_t* Vt, bf16_t* MIX, int b, int h, int qb, char* lds, int tid_in) {
;     ...
;             if (kv0 + 127 > q0 + 32 * wave) {
; #pragma unroll
;                 for (int kb = 0; kb < 4; ++kb)
; #pragma unroll
;                     for (int i = 0; i < 16; ++i) { const int kv = kv0 + 32 * kb + crow(i, hh); if (kv > qabs) p[kb][i] = -1e30f; }
	v_cndmask_b32_e32 v95, v208, v95, vcc
	v_cmp_le_i32_e32 vcc, v191, v170
	v_add_u32_e32 v191, 27, v190
	s_nop 0
	v_cndmask_b32_e32 v96, v208, v96, vcc
	v_cmp_le_i32_e32 vcc, v191, v170
	v_add_u32_e32 v191, 32, v190
	s_nop 0
	v_cndmask_b32_e32 v97, v208, v97, vcc
	v_cmp_lt_i32_e32 vcc, v191, v170
	s_nop 1
	v_cndmask_b32_e32 v67, v208, v67, vcc
	v_cmp_le_i32_e32 vcc, v191, v170
	v_add_u32_e32 v191, 34, v190
	s_nop 0
	v_cndmask_b32_e32 v66, v208, v66, vcc
	v_cmp_le_i32_e32 vcc, v191, v170
	v_add_u32_e32 v191, 35, v190
	s_nop 0
	v_cndmask_b32_e32 v68, v208, v68, vcc
	v_cmp_le_i32_e32 vcc, v191, v170
	v_add_u32_e32 v191, 40, v190
	s_nop 0
	v_cndmask_b32_e32 v69, v208, v69, vcc
	v_cmp_le_i32_e32 vcc, v191, v170
	v_add_u32_e32 v191, 41, v190
	s_nop 0
	v_cndmask_b32_e32 v70, v208, v70, vcc
	v_cmp_le_i32_e32 vcc, v191, v170
	v_add_u32_e32 v191, 42, v190
	s_nop 0
	v_cndmask_b32_e32 v71, v208, v71, vcc
	v_cmp_le_i32_e32 vcc, v191, v170
	v_add_u32_e32 v191, 43, v190
	s_nop 0
	v_cndmask_b32_e32 v72, v208, v72, vcc
	v_cmp_le_i32_e32 vcc, v191, v170
	v_add_u32_e32 v191, 48, v190
	s_nop 0
	v_cndmask_b32_e32 v73, v208, v73, vcc
	v_cmp_le_i32_e32 vcc, v191, v170
	v_add_u32_e32 v191, 49, v190
	s_nop 0
	v_cndmask_b32_e32 v74, v208, v74, vcc
	v_cmp_le_i32_e32 vcc, v191, v170
	v_add_u32_e32 v191, 50, v190
	s_nop 0
	v_cndmask_b32_e32 v75, v208, v75, vcc
	v_cmp_le_i32_e32 vcc, v191, v170
	v_add_u32_e32 v191, 51, v190
	s_nop 0
	v_cndmask_b32_e32 v76, v208, v76, vcc
	v_cmp_le_i32_e32 vcc, v191, v170
	v_add_u32_e32 v191, 56, v190
	s_nop 0
	v_cndmask_b32_e32 v77, v208, v77, vcc
	v_cmp_le_i32_e32 vcc, v191, v170
	v_add_u32_e32 v191, 57, v190
	s_nop 0
	v_cndmask_b32_e32 v78, v208, v78, vcc
	v_cmp_le_i32_e32 vcc, v191, v170
	v_add_u32_e32 v191, 58, v190
	s_nop 0
	v_cndmask_b32_e32 v79, v208, v79, vcc
	v_cmp_le_i32_e32 vcc, v191, v170
	v_add_u32_e32 v191, 59, v190
	s_nop 0
	v_cndmask_b32_e32 v80, v208, v80, vcc
	v_cmp_le_i32_e32 vcc, v191, v170
	v_add_u32_e32 v191, 64, v190
	s_nop 0
	v_cndmask_b32_e32 v81, v208, v81, vcc
	v_cmp_lt_i32_e32 vcc, v191, v170
	s_nop 1
	v_cndmask_b32_e32 v51, v208, v51, vcc
	v_cmp_le_i32_e32 vcc, v191, v170
	v_add_u32_e32 v191, 0x42, v190
	s_nop 0
	v_cndmask_b32_e32 v50, v208, v50, vcc
	v_cmp_le_i32_e32 vcc, v191, v170
	v_add_u32_e32 v191, 0x43, v190
	s_nop 0
	v_cndmask_b32_e32 v52, v208, v52, vcc
	v_cmp_le_i32_e32 vcc, v191, v170
	v_add_u32_e32 v191, 0x48, v190
	s_nop 0
	v_cndmask_b32_e32 v53, v208, v53, vcc
	v_cmp_le_i32_e32 vcc, v191, v170
	v_add_u32_e32 v191, 0x49, v190
	s_nop 0
	v_cndmask_b32_e32 v54, v208, v54, vcc
	v_cmp_le_i32_e32 vcc, v191, v170
	v_add_u32_e32 v191, 0x4a, v190
	s_nop 0
	v_cndmask_b32_e32 v55, v208, v55, vcc
	v_cmp_le_i32_e32 vcc, v191, v170
	v_add_u32_e32 v191, 0x4b, v190
	s_nop 0
	v_cndmask_b32_e32 v56, v208, v56, vcc
	v_cmp_le_i32_e32 vcc, v191, v170
	v_add_u32_e32 v191, 0x50, v190
	s_nop 0
	v_cndmask_b32_e32 v57, v208, v57, vcc
	v_cmp_le_i32_e32 vcc, v191, v170
	v_add_u32_e32 v191, 0x51, v190
	s_nop 0
	v_cndmask_b32_e32 v58, v208, v58, vcc
	v_cmp_le_i32_e32 vcc, v191, v170
	v_add_u32_e32 v191, 0x52, v190
	s_nop 0
	v_cndmask_b32_e32 v59, v208, v59, vcc
	v_cmp_le_i32_e32 vcc, v191, v170
	v_add_u32_e32 v191, 0x53, v190
	s_nop 0
	v_cndmask_b32_e32 v60, v208, v60, vcc
	v_cmp_le_i32_e32 vcc, v191, v170
	v_add_u32_e32 v191, 0x58, v190
	s_nop 0
	v_cndmask_b32_e32 v61, v208, v61, vcc
	v_cmp_le_i32_e32 vcc, v191, v170
	v_add_u32_e32 v191, 0x59, v190
	s_nop 0
	v_cndmask_b32_e32 v62, v208, v62, vcc
	v_cmp_le_i32_e32 vcc, v191, v170
	v_add_u32_e32 v191, 0x5a, v190
	s_nop 0
	v_cndmask_b32_e32 v63, v208, v63, vcc
	v_cmp_le_i32_e32 vcc, v191, v170
	v_add_u32_e32 v191, 0x5b, v190
	s_nop 0
	v_cndmask_b32_e32 v64, v208, v64, vcc
	v_cmp_le_i32_e32 vcc, v191, v170
	v_add_u32_e32 v191, 0x60, v190
	s_nop 0
	v_cndmask_b32_e32 v65, v208, v65, vcc
	v_cmp_lt_i32_e32 vcc, v191, v170
	s_nop 1
	v_cndmask_b32_e32 v35, v208, v35, vcc
	v_cmp_le_i32_e32 vcc, v191, v170
	v_add_u32_e32 v191, 0x62, v190
	s_nop 0
	v_cndmask_b32_e32 v34, v208, v34, vcc
	v_cmp_le_i32_e32 vcc, v191, v170
	v_add_u32_e32 v191, 0x63, v190
	s_nop 0
	v_cndmask_b32_e32 v36, v208, v36, vcc
	v_cmp_le_i32_e32 vcc, v191, v170
	v_add_u32_e32 v191, 0x68, v190
	s_nop 0
	v_cndmask_b32_e32 v37, v208, v37, vcc
	v_cmp_le_i32_e32 vcc, v191, v170
	v_add_u32_e32 v191, 0x69, v190
	s_nop 0
	v_cndmask_b32_e32 v38, v208, v38, vcc
	v_cmp_le_i32_e32 vcc, v191, v170
	v_add_u32_e32 v191, 0x6a, v190
	s_nop 0
	v_cndmask_b32_e32 v39, v208, v39, vcc
	v_cmp_le_i32_e32 vcc, v191, v170
	v_add_u32_e32 v191, 0x6b, v190
	s_nop 0
	v_cndmask_b32_e32 v40, v208, v40, vcc
	v_cmp_le_i32_e32 vcc, v191, v170
	v_add_u32_e32 v191, 0x70, v190
	s_nop 0
	v_cndmask_b32_e32 v41, v208, v41, vcc
	v_cmp_le_i32_e32 vcc, v191, v170
	v_add_u32_e32 v191, 0x71, v190
	s_nop 0
	v_cndmask_b32_e32 v42, v208, v42, vcc
	v_cmp_le_i32_e32 vcc, v191, v170
	v_add_u32_e32 v191, 0x72, v190
	s_nop 0
	v_cndmask_b32_e32 v43, v208, v43, vcc
	v_cmp_le_i32_e32 vcc, v191, v170
	v_add_u32_e32 v191, 0x73, v190
	s_nop 0
	v_cndmask_b32_e32 v44, v208, v44, vcc
	v_cmp_le_i32_e32 vcc, v191, v170
	v_add_u32_e32 v191, 0x78, v190
	s_nop 0
	v_cndmask_b32_e32 v45, v208, v45, vcc
	v_cmp_le_i32_e32 vcc, v191, v170
	v_add_u32_e32 v191, 0x79, v190
	s_nop 0
	v_cndmask_b32_e32 v46, v208, v46, vcc
	v_cmp_le_i32_e32 vcc, v191, v170
	v_add_u32_e32 v191, 0x7a, v190
	v_add_u32_e32 v190, 0x7b, v190
	v_cndmask_b32_e32 v47, v208, v47, vcc
	v_cmp_le_i32_e32 vcc, v191, v170
	s_nop 1
	v_cndmask_b32_e32 v48, v208, v48, vcc
	v_cmp_le_i32_e32 vcc, v190, v170
	s_nop 1
	v_cndmask_b32_e32 v49, v208, v49, vcc
